# grid barrier: generation taken as the site's constant ordinal instead of the reciprocal division after each arrive atomic (5 static barriers)
# speedup vs baseline: 1.0066x; 1.0027x over previous
;     __device__ __forceinline__ const char* b(const Unit& u) const { return (const char*)Bt + (size_t)u.pn * 2 * hB() + (size_t)(u.pm >> gshift) * goff; }
;     __device__ __forceinline__ const char* b(const Unit& u) const { return (const char*)Bt + (size_t)((u.pn >> 4) * 4096 + (u.pn & 15) * 16) * 1024 * 2 + (size_t)(u.pm >> 1) * 512; }
;     __device__ __forceinline__ const char* b(const Unit& u) const { return (const char*)Bt + ((size_t)(((u.pm >> 4) * 1024 + u.pn * 256) * 16 + (u.pm & 15)) * 512) * 2; }
; __device__ __forceinline__ unsigned xb_ld(unsigned* p)              { return __hip_atomic_load(p, __ATOMIC_RELAXED, __HIP_MEMORY_SCOPE_AGENT); }
; __device__ __forceinline__ unsigned xb_add(unsigned* p, unsigned v) { return __hip_atomic_fetch_add(p, v, __ATOMIC_RELAXED, __HIP_MEMORY_SCOPE_AGENT); }
; #define XB_SPIN(cond, bar) do { unsigned _sp = 0; while (cond) { __builtin_amdgcn_s_sleep(1); \
;     if ((++_sp & 255u) == 0u) { if (xb_ld(&(bar)[XB_TMO])) break; if (_sp > XB_SPIN_CAP) { atomicAdd(&(bar)[XB_TMO], 1u); break; } } } } while (0)
; __device__ __forceinline__ void xcd_barrier(const XcdBarrier& b, const int wave) {
;     ...
;         const unsigned old = xb_add(&bar[XB_XSUB(b.x)], 1u);
;         const unsigned gen = old / nloc;
;         if (old + 1u == (gen + 1u) * nloc) {
;             __builtin_amdgcn_fence(__ATOMIC_RELEASE, "agent");
;             asm volatile("s_waitcnt vmcnt(0)" ::: "memory");
;             const unsigned og = xb_add(&bar[XB_TOP], 1u);
;             const unsigned tg = og / nx;
;             if (og + 1u == (tg + 1u) * nx) xb_add(&bar[XB_TOPGEN], 1u);
;             else XB_SPIN(xb_ld(&bar[XB_TOPGEN]) == tg, bar);
;             __builtin_amdgcn_fence(__ATOMIC_ACQUIRE, "agent");
;             xb_add(&bar[XB_XGEN(b.x)], 1u);
;             asm volatile("s_waitcnt vmcnt(0)" ::: "memory");
;         } else {
;             XB_SPIN(xb_ld(&bar[XB_XGEN(b.x)]) == gen, bar);
.LBB0_128:
	s_or_b64 exec, exec, s[10:11]
	s_waitcnt vmcnt(0)
	v_readfirstlane_b32 s8, v3
	v_add_u32_e32 v5, s8, v1
	v_add_u32_e32 v3, 1, v5
	v_mov_b32_e32 v1, 0
	v_mul_u32_u24_e32 v2, 1, v2
	v_cmp_ne_u32_e32 vcc, v3, v2
	s_and_saveexec_b64 s[8:9], vcc
	s_xor_b64 s[8:9], exec, s[8:9]
	s_cbranch_execz .LBB0_142
	s_waitcnt lgkmcnt(0)
	s_add_u32 s16, s94, 0x7500
	s_addc_u32 s17, s95, 0
	v_mov_b32_e32 v0, 0
	global_load_dword v0, v0, s[16:17] sc1
	s_waitcnt vmcnt(0)
	v_cmp_eq_u32_e32 vcc, v0, v1
	s_and_saveexec_b64 s[10:11], vcc
	s_cbranch_execz .LBB0_141
	s_add_u32 s12, s94, 0x4200
	s_addc_u32 s13, s95, 0
	s_mov_b32 s14, 1
	s_mov_b64 s[18:19], 0
	v_mov_b32_e32 v0, 0
	s_branch .LBB0_132

; __device__ __forceinline__ unsigned xb_ld(unsigned* p)              { return __hip_atomic_load(p, __ATOMIC_RELAXED, __HIP_MEMORY_SCOPE_AGENT); }
; __device__ __forceinline__ unsigned xb_add(unsigned* p, unsigned v) { return __hip_atomic_fetch_add(p, v, __ATOMIC_RELAXED, __HIP_MEMORY_SCOPE_AGENT); }
; #define XB_SPIN(cond, bar) do { unsigned _sp = 0; while (cond) { __builtin_amdgcn_s_sleep(1); \
;     if ((++_sp & 255u) == 0u) { if (xb_ld(&(bar)[XB_TMO])) break; if (_sp > XB_SPIN_CAP) { atomicAdd(&(bar)[XB_TMO], 1u); break; } } } } while (0)
; __device__ __forceinline__ void xcd_barrier(const XcdBarrier& b, const int wave) {
;     ...
;             const unsigned og = xb_add(&bar[XB_TOP], 1u);
;             const unsigned tg = og / nx;
;             if (og + 1u == (tg + 1u) * nx) xb_add(&bar[XB_TOPGEN], 1u);
;             else XB_SPIN(xb_ld(&bar[XB_TOPGEN]) == tg, bar);
.LBB0_145:
	s_or_b64 exec, exec, s[10:11]
	s_waitcnt vmcnt(0)
	v_readfirstlane_b32 s8, v2
	s_add_u32 s10, s94, 0x7500
	s_addc_u32 s11, s95, 0
	s_mov_b64 s[12:13], -1
	v_add_u32_e32 v1, s8, v1
	v_add_u32_e32 v4, 1, v1
	v_mov_b32_e32 v2, 0
	v_mul_u32_u24_e32 v0, 1, v0
	v_cmp_ne_u32_e32 vcc, v4, v0
	v_mov_b64_e32 v[0:1], s[10:11]
	s_and_saveexec_b64 s[8:9], vcc
	s_cbranch_execz .LBB0_157
	v_mov_b32_e32 v0, 0
	global_load_dword v1, v0, s[10:11] sc1
	s_mov_b64 s[18:19], 0
	s_waitcnt vmcnt(0)
	v_cmp_eq_u32_e32 vcc, v1, v2
	s_and_saveexec_b64 s[16:17], vcc
	s_cbranch_execz .LBB0_156
	s_add_u32 s12, s94, 0x4200
	s_addc_u32 s13, s95, 0
	s_mov_b32 s14, 1
	s_branch .LBB0_149

;     __device__ __forceinline__ const char* b(const Unit& u) const { return (const char*)Bt + (size_t)u.pn * 2 * hB() + (size_t)(u.pm >> gshift) * goff; }
;     __device__ __forceinline__ const char* b(const Unit& u) const { return (const char*)Bt + (size_t)((u.pn >> 4) * 4096 + (u.pn & 15) * 16) * 1024 * 2 + (size_t)(u.pm >> 1) * 512; }
;     __device__ __forceinline__ const char* b(const Unit& u) const { return (const char*)Bt + ((size_t)(((u.pm >> 4) * 1024 + u.pn * 256) * 16 + (u.pm & 15)) * 512) * 2; }
; __device__ __forceinline__ unsigned xb_ld(unsigned* p)              { return __hip_atomic_load(p, __ATOMIC_RELAXED, __HIP_MEMORY_SCOPE_AGENT); }
; __device__ __forceinline__ unsigned xb_add(unsigned* p, unsigned v) { return __hip_atomic_fetch_add(p, v, __ATOMIC_RELAXED, __HIP_MEMORY_SCOPE_AGENT); }
; #define XB_SPIN(cond, bar) do { unsigned _sp = 0; while (cond) { __builtin_amdgcn_s_sleep(1); \
;     if ((++_sp & 255u) == 0u) { if (xb_ld(&(bar)[XB_TMO])) break; if (_sp > XB_SPIN_CAP) { atomicAdd(&(bar)[XB_TMO], 1u); break; } } } } while (0)
; __device__ __forceinline__ void xcd_barrier(const XcdBarrier& b, const int wave) {
;     ...
;         const unsigned old = xb_add(&bar[XB_XSUB(b.x)], 1u);
;         const unsigned gen = old / nloc;
;         if (old + 1u == (gen + 1u) * nloc) {
;             __builtin_amdgcn_fence(__ATOMIC_RELEASE, "agent");
;             asm volatile("s_waitcnt vmcnt(0)" ::: "memory");
;             const unsigned og = xb_add(&bar[XB_TOP], 1u);
;             const unsigned tg = og / nx;
;             if (og + 1u == (tg + 1u) * nx) xb_add(&bar[XB_TOPGEN], 1u);
;             else XB_SPIN(xb_ld(&bar[XB_TOPGEN]) == tg, bar);
;             __builtin_amdgcn_fence(__ATOMIC_ACQUIRE, "agent");
;             xb_add(&bar[XB_XGEN(b.x)], 1u);
;             asm volatile("s_waitcnt vmcnt(0)" ::: "memory");
;         } else {
;             XB_SPIN(xb_ld(&bar[XB_XGEN(b.x)]) == gen, bar);
.LBB0_304:
	s_or_b64 exec, exec, s[8:9]
	s_waitcnt vmcnt(0)
	v_readfirstlane_b32 s6, v3
	v_add_u32_e32 v5, s6, v1
	v_add_u32_e32 v3, 1, v5
	v_mov_b32_e32 v1, 1
	v_mul_u32_u24_e32 v2, 2, v2
	v_cmp_ne_u32_e32 vcc, v3, v2
	s_and_saveexec_b64 s[6:7], vcc
	s_xor_b64 s[6:7], exec, s[6:7]
	s_cbranch_execz .LBB0_318
	s_waitcnt lgkmcnt(0)
	s_add_u32 s12, s94, 0x7500
	s_addc_u32 s13, s95, 0
	v_mov_b32_e32 v0, 0
	global_load_dword v0, v0, s[12:13] sc1
	s_waitcnt vmcnt(0)
	v_cmp_eq_u32_e32 vcc, v0, v1
	s_and_saveexec_b64 s[8:9], vcc
	s_cbranch_execz .LBB0_317
	s_add_u32 s10, s94, 0x4200
	s_addc_u32 s11, s95, 0
	s_mov_b32 s14, 1
	s_mov_b64 s[16:17], 0
	v_mov_b32_e32 v0, 0
	s_branch .LBB0_308

; __device__ __forceinline__ unsigned xb_ld(unsigned* p)              { return __hip_atomic_load(p, __ATOMIC_RELAXED, __HIP_MEMORY_SCOPE_AGENT); }
; __device__ __forceinline__ unsigned xb_add(unsigned* p, unsigned v) { return __hip_atomic_fetch_add(p, v, __ATOMIC_RELAXED, __HIP_MEMORY_SCOPE_AGENT); }
; #define XB_SPIN(cond, bar) do { unsigned _sp = 0; while (cond) { __builtin_amdgcn_s_sleep(1); \
;     if ((++_sp & 255u) == 0u) { if (xb_ld(&(bar)[XB_TMO])) break; if (_sp > XB_SPIN_CAP) { atomicAdd(&(bar)[XB_TMO], 1u); break; } } } } while (0)
; __device__ __forceinline__ void xcd_barrier(const XcdBarrier& b, const int wave) {
;     ...
;             const unsigned og = xb_add(&bar[XB_TOP], 1u);
;             const unsigned tg = og / nx;
;             if (og + 1u == (tg + 1u) * nx) xb_add(&bar[XB_TOPGEN], 1u);
;             else XB_SPIN(xb_ld(&bar[XB_TOPGEN]) == tg, bar);
.LBB0_321:
	s_or_b64 exec, exec, s[8:9]
	s_waitcnt vmcnt(0)
	v_readfirstlane_b32 s6, v2
	s_add_u32 s8, s94, 0x7500
	s_addc_u32 s9, s95, 0
	s_mov_b64 s[10:11], -1
	v_add_u32_e32 v1, s6, v1
	v_add_u32_e32 v4, 1, v1
	v_mov_b32_e32 v2, 1
	v_mul_u32_u24_e32 v0, 2, v0
	v_cmp_ne_u32_e32 vcc, v4, v0
	v_mov_b64_e32 v[0:1], s[8:9]
	s_and_saveexec_b64 s[6:7], vcc
	s_cbranch_execz .LBB0_333
	v_mov_b32_e32 v0, 0
	global_load_dword v1, v0, s[8:9] sc1
	s_mov_b64 s[16:17], 0
	s_waitcnt vmcnt(0)
	v_cmp_eq_u32_e32 vcc, v1, v2
	s_and_saveexec_b64 s[12:13], vcc
	s_cbranch_execz .LBB0_332
	s_add_u32 s10, s94, 0x4200
	s_addc_u32 s11, s95, 0
	s_mov_b32 s14, 1
	s_branch .LBB0_325

;     __device__ __forceinline__ const char* b(const Unit& u) const { return (const char*)Bt + (size_t)u.pn * 2 * hB() + (size_t)(u.pm >> gshift) * goff; }
;     __device__ __forceinline__ const char* b(const Unit& u) const { return (const char*)Bt + (size_t)((u.pn >> 4) * 4096 + (u.pn & 15) * 16) * 1024 * 2 + (size_t)(u.pm >> 1) * 512; }
;     __device__ __forceinline__ const char* b(const Unit& u) const { return (const char*)Bt + ((size_t)(((u.pm >> 4) * 1024 + u.pn * 256) * 16 + (u.pm & 15)) * 512) * 2; }
; __device__ __forceinline__ unsigned xb_ld(unsigned* p)              { return __hip_atomic_load(p, __ATOMIC_RELAXED, __HIP_MEMORY_SCOPE_AGENT); }
; __device__ __forceinline__ unsigned xb_add(unsigned* p, unsigned v) { return __hip_atomic_fetch_add(p, v, __ATOMIC_RELAXED, __HIP_MEMORY_SCOPE_AGENT); }
; #define XB_SPIN(cond, bar) do { unsigned _sp = 0; while (cond) { __builtin_amdgcn_s_sleep(1); \
;     if ((++_sp & 255u) == 0u) { if (xb_ld(&(bar)[XB_TMO])) break; if (_sp > XB_SPIN_CAP) { atomicAdd(&(bar)[XB_TMO], 1u); break; } } } } while (0)
; __device__ __forceinline__ void xcd_barrier(const XcdBarrier& b, const int wave) {
;     ...
;         const unsigned old = xb_add(&bar[XB_XSUB(b.x)], 1u);
;         const unsigned gen = old / nloc;
;         if (old + 1u == (gen + 1u) * nloc) {
;             __builtin_amdgcn_fence(__ATOMIC_RELEASE, "agent");
;             asm volatile("s_waitcnt vmcnt(0)" ::: "memory");
;             const unsigned og = xb_add(&bar[XB_TOP], 1u);
;             const unsigned tg = og / nx;
;             if (og + 1u == (tg + 1u) * nx) xb_add(&bar[XB_TOPGEN], 1u);
;             else XB_SPIN(xb_ld(&bar[XB_TOPGEN]) == tg, bar);
;             __builtin_amdgcn_fence(__ATOMIC_ACQUIRE, "agent");
;             xb_add(&bar[XB_XGEN(b.x)], 1u);
;             asm volatile("s_waitcnt vmcnt(0)" ::: "memory");
;         } else {
;             XB_SPIN(xb_ld(&bar[XB_XGEN(b.x)]) == gen, bar);
.LBB0_436:
	s_or_b64 exec, exec, s[10:11]
	s_waitcnt vmcnt(0)
	v_readfirstlane_b32 s8, v3
	v_add_u32_e32 v5, s8, v1
	v_add_u32_e32 v3, 1, v5
	v_mov_b32_e32 v1, 2
	v_mul_u32_u24_e32 v2, 3, v2
	v_cmp_ne_u32_e32 vcc, v3, v2
	s_and_saveexec_b64 s[8:9], vcc
	s_xor_b64 s[8:9], exec, s[8:9]
	s_cbranch_execz .LBB0_450
	s_waitcnt lgkmcnt(0)
	s_add_u32 s16, s94, 0x7500
	s_addc_u32 s17, s95, 0
	v_mov_b32_e32 v0, 0
	global_load_dword v0, v0, s[16:17] sc1
	s_waitcnt vmcnt(0)
	v_cmp_eq_u32_e32 vcc, v0, v1
	s_and_saveexec_b64 s[10:11], vcc
	s_cbranch_execz .LBB0_449
	s_add_u32 s12, s94, 0x4200
	s_addc_u32 s13, s95, 0
	s_mov_b32 s14, 1
	s_mov_b64 s[18:19], 0
	v_mov_b32_e32 v0, 0
	s_branch .LBB0_440

; __device__ __forceinline__ unsigned xb_ld(unsigned* p)              { return __hip_atomic_load(p, __ATOMIC_RELAXED, __HIP_MEMORY_SCOPE_AGENT); }
; __device__ __forceinline__ unsigned xb_add(unsigned* p, unsigned v) { return __hip_atomic_fetch_add(p, v, __ATOMIC_RELAXED, __HIP_MEMORY_SCOPE_AGENT); }
; #define XB_SPIN(cond, bar) do { unsigned _sp = 0; while (cond) { __builtin_amdgcn_s_sleep(1); \
;     if ((++_sp & 255u) == 0u) { if (xb_ld(&(bar)[XB_TMO])) break; if (_sp > XB_SPIN_CAP) { atomicAdd(&(bar)[XB_TMO], 1u); break; } } } } while (0)
; __device__ __forceinline__ void xcd_barrier(const XcdBarrier& b, const int wave) {
;     ...
;             const unsigned og = xb_add(&bar[XB_TOP], 1u);
;             const unsigned tg = og / nx;
;             if (og + 1u == (tg + 1u) * nx) xb_add(&bar[XB_TOPGEN], 1u);
;             else XB_SPIN(xb_ld(&bar[XB_TOPGEN]) == tg, bar);
.LBB0_453:
	s_or_b64 exec, exec, s[10:11]
	s_waitcnt vmcnt(0)
	v_readfirstlane_b32 s8, v2
	s_add_u32 s10, s94, 0x7500
	s_addc_u32 s11, s95, 0
	s_mov_b64 s[12:13], -1
	v_add_u32_e32 v1, s8, v1
	v_add_u32_e32 v4, 1, v1
	v_mov_b32_e32 v2, 2
	v_mul_u32_u24_e32 v0, 3, v0
	v_cmp_ne_u32_e32 vcc, v4, v0
	v_mov_b64_e32 v[0:1], s[10:11]
	s_and_saveexec_b64 s[8:9], vcc
	s_cbranch_execz .LBB0_465
	v_mov_b32_e32 v0, 0
	global_load_dword v1, v0, s[10:11] sc1
	s_mov_b64 s[18:19], 0
	s_waitcnt vmcnt(0)
	v_cmp_eq_u32_e32 vcc, v1, v2
	s_and_saveexec_b64 s[16:17], vcc
	s_cbranch_execz .LBB0_464
	s_add_u32 s12, s94, 0x4200
	s_addc_u32 s13, s95, 0
	s_mov_b32 s14, 1
	s_branch .LBB0_457

;     __device__ __forceinline__ const char* b(const Unit& u) const { return (const char*)Bt + (size_t)u.pn * 2 * hB() + (size_t)(u.pm >> gshift) * goff; }
;     __device__ __forceinline__ const char* b(const Unit& u) const { return (const char*)Bt + (size_t)((u.pn >> 4) * 4096 + (u.pn & 15) * 16) * 1024 * 2 + (size_t)(u.pm >> 1) * 512; }
;     __device__ __forceinline__ const char* b(const Unit& u) const { return (const char*)Bt + ((size_t)(((u.pm >> 4) * 1024 + u.pn * 256) * 16 + (u.pm & 15)) * 512) * 2; }
; __device__ __forceinline__ unsigned xb_ld(unsigned* p)              { return __hip_atomic_load(p, __ATOMIC_RELAXED, __HIP_MEMORY_SCOPE_AGENT); }
; __device__ __forceinline__ unsigned xb_add(unsigned* p, unsigned v) { return __hip_atomic_fetch_add(p, v, __ATOMIC_RELAXED, __HIP_MEMORY_SCOPE_AGENT); }
; #define XB_SPIN(cond, bar) do { unsigned _sp = 0; while (cond) { __builtin_amdgcn_s_sleep(1); \
;     if ((++_sp & 255u) == 0u) { if (xb_ld(&(bar)[XB_TMO])) break; if (_sp > XB_SPIN_CAP) { atomicAdd(&(bar)[XB_TMO], 1u); break; } } } } while (0)
; __device__ __forceinline__ void xcd_barrier(const XcdBarrier& b, const int wave) {
;     ...
;         const unsigned old = xb_add(&bar[XB_XSUB(b.x)], 1u);
;         const unsigned gen = old / nloc;
;         if (old + 1u == (gen + 1u) * nloc) {
;             __builtin_amdgcn_fence(__ATOMIC_RELEASE, "agent");
;             asm volatile("s_waitcnt vmcnt(0)" ::: "memory");
;             const unsigned og = xb_add(&bar[XB_TOP], 1u);
;             const unsigned tg = og / nx;
;             if (og + 1u == (tg + 1u) * nx) xb_add(&bar[XB_TOPGEN], 1u);
;             else XB_SPIN(xb_ld(&bar[XB_TOPGEN]) == tg, bar);
;             __builtin_amdgcn_fence(__ATOMIC_ACQUIRE, "agent");
;             xb_add(&bar[XB_XGEN(b.x)], 1u);
;             asm volatile("s_waitcnt vmcnt(0)" ::: "memory");
;         } else {
;             XB_SPIN(xb_ld(&bar[XB_XGEN(b.x)]) == gen, bar);
.LBB0_563:
	s_or_b64 exec, exec, s[8:9]
	s_waitcnt vmcnt(0)
	v_readfirstlane_b32 s6, v3
	v_add_u32_e32 v5, s6, v1
	v_add_u32_e32 v3, 1, v5
	v_mov_b32_e32 v1, 3
	v_mul_u32_u24_e32 v2, 4, v2
	v_cmp_ne_u32_e32 vcc, v3, v2
	s_and_saveexec_b64 s[6:7], vcc
	s_xor_b64 s[6:7], exec, s[6:7]
	s_cbranch_execz .LBB0_577
	s_waitcnt lgkmcnt(0)
	s_add_u32 s12, s94, 0x7500
	s_addc_u32 s13, s95, 0
	v_mov_b32_e32 v0, 0
	global_load_dword v0, v0, s[12:13] sc1
	s_waitcnt vmcnt(0)
	v_cmp_eq_u32_e32 vcc, v0, v1
	s_and_saveexec_b64 s[8:9], vcc
	s_cbranch_execz .LBB0_576
	s_add_u32 s10, s94, 0x4200
	s_addc_u32 s11, s95, 0
	s_mov_b32 s14, 1
	s_mov_b64 s[16:17], 0
	v_mov_b32_e32 v0, 0
	s_branch .LBB0_567

; __device__ __forceinline__ unsigned xb_ld(unsigned* p)              { return __hip_atomic_load(p, __ATOMIC_RELAXED, __HIP_MEMORY_SCOPE_AGENT); }
; __device__ __forceinline__ unsigned xb_add(unsigned* p, unsigned v) { return __hip_atomic_fetch_add(p, v, __ATOMIC_RELAXED, __HIP_MEMORY_SCOPE_AGENT); }
; #define XB_SPIN(cond, bar) do { unsigned _sp = 0; while (cond) { __builtin_amdgcn_s_sleep(1); \
;     if ((++_sp & 255u) == 0u) { if (xb_ld(&(bar)[XB_TMO])) break; if (_sp > XB_SPIN_CAP) { atomicAdd(&(bar)[XB_TMO], 1u); break; } } } } while (0)
; __device__ __forceinline__ void xcd_barrier(const XcdBarrier& b, const int wave) {
;     ...
;             const unsigned og = xb_add(&bar[XB_TOP], 1u);
;             const unsigned tg = og / nx;
;             if (og + 1u == (tg + 1u) * nx) xb_add(&bar[XB_TOPGEN], 1u);
;             else XB_SPIN(xb_ld(&bar[XB_TOPGEN]) == tg, bar);
.LBB0_580:
	s_or_b64 exec, exec, s[8:9]
	s_waitcnt vmcnt(0)
	v_readfirstlane_b32 s6, v2
	s_add_u32 s8, s94, 0x7500
	s_addc_u32 s9, s95, 0
	s_mov_b64 s[10:11], -1
	v_add_u32_e32 v1, s6, v1
	v_add_u32_e32 v4, 1, v1
	v_mov_b32_e32 v2, 3
	v_mul_u32_u24_e32 v0, 4, v0
	v_cmp_ne_u32_e32 vcc, v4, v0
	v_mov_b64_e32 v[0:1], s[8:9]
	s_and_saveexec_b64 s[6:7], vcc
	s_cbranch_execz .LBB0_592
	v_mov_b32_e32 v0, 0
	global_load_dword v1, v0, s[8:9] sc1
	s_mov_b64 s[16:17], 0
	s_waitcnt vmcnt(0)
	v_cmp_eq_u32_e32 vcc, v1, v2
	s_and_saveexec_b64 s[12:13], vcc
	s_cbranch_execz .LBB0_591
	s_add_u32 s10, s94, 0x4200
	s_addc_u32 s11, s95, 0
	s_mov_b32 s14, 1
	s_branch .LBB0_584

;     __device__ __forceinline__ const char* b(const Unit& u) const { return (const char*)Bt + (size_t)u.pn * 2 * hB() + (size_t)(u.pm >> gshift) * goff; }
;     __device__ __forceinline__ const char* b(const Unit& u) const { return (const char*)Bt + (size_t)((u.pn >> 4) * 4096 + (u.pn & 15) * 16) * 1024 * 2 + (size_t)(u.pm >> 1) * 512; }
;     __device__ __forceinline__ const char* b(const Unit& u) const { return (const char*)Bt + ((size_t)(((u.pm >> 4) * 1024 + u.pn * 256) * 16 + (u.pm & 15)) * 512) * 2; }
; __device__ __forceinline__ unsigned xb_ld(unsigned* p)              { return __hip_atomic_load(p, __ATOMIC_RELAXED, __HIP_MEMORY_SCOPE_AGENT); }
; __device__ __forceinline__ unsigned xb_add(unsigned* p, unsigned v) { return __hip_atomic_fetch_add(p, v, __ATOMIC_RELAXED, __HIP_MEMORY_SCOPE_AGENT); }
; #define XB_SPIN(cond, bar) do { unsigned _sp = 0; while (cond) { __builtin_amdgcn_s_sleep(1); \
;     if ((++_sp & 255u) == 0u) { if (xb_ld(&(bar)[XB_TMO])) break; if (_sp > XB_SPIN_CAP) { atomicAdd(&(bar)[XB_TMO], 1u); break; } } } } while (0)
; __device__ __forceinline__ void xcd_barrier(const XcdBarrier& b, const int wave) {
;     ...
;         const unsigned old = xb_add(&bar[XB_XSUB(b.x)], 1u);
;         const unsigned gen = old / nloc;
;         if (old + 1u == (gen + 1u) * nloc) {
;             __builtin_amdgcn_fence(__ATOMIC_RELEASE, "agent");
;             asm volatile("s_waitcnt vmcnt(0)" ::: "memory");
;             const unsigned og = xb_add(&bar[XB_TOP], 1u);
;             const unsigned tg = og / nx;
;             if (og + 1u == (tg + 1u) * nx) xb_add(&bar[XB_TOPGEN], 1u);
;             else XB_SPIN(xb_ld(&bar[XB_TOPGEN]) == tg, bar);
;             __builtin_amdgcn_fence(__ATOMIC_ACQUIRE, "agent");
;             xb_add(&bar[XB_XGEN(b.x)], 1u);
;             asm volatile("s_waitcnt vmcnt(0)" ::: "memory");
;         } else {
;             XB_SPIN(xb_ld(&bar[XB_XGEN(b.x)]) == gen, bar);
.LBB0_665:
	s_or_b64 exec, exec, s[8:9]
	s_waitcnt vmcnt(0)
	v_readfirstlane_b32 s6, v3
	v_add_u32_e32 v5, s6, v1
	v_add_u32_e32 v3, 1, v5
	v_mov_b32_e32 v1, 4
	v_mul_u32_u24_e32 v2, 5, v2
	v_cmp_ne_u32_e32 vcc, v3, v2
	s_and_saveexec_b64 s[6:7], vcc
	s_xor_b64 s[6:7], exec, s[6:7]
	s_cbranch_execz .LBB0_679
	s_waitcnt lgkmcnt(0)
	s_add_u32 s12, s94, 0x7500
	s_addc_u32 s13, s95, 0
	v_mov_b32_e32 v0, 0
	global_load_dword v0, v0, s[12:13] sc1
	s_waitcnt vmcnt(0)
	v_cmp_eq_u32_e32 vcc, v0, v1
	s_and_saveexec_b64 s[8:9], vcc
	s_cbranch_execz .LBB0_678
	s_add_u32 s10, s94, 0x4200
	s_addc_u32 s11, s95, 0
	s_mov_b32 s24, 1
	s_mov_b64 s[14:15], 0
	v_mov_b32_e32 v0, 0
	s_branch .LBB0_669

; __device__ __forceinline__ unsigned xb_ld(unsigned* p)              { return __hip_atomic_load(p, __ATOMIC_RELAXED, __HIP_MEMORY_SCOPE_AGENT); }
; __device__ __forceinline__ unsigned xb_add(unsigned* p, unsigned v) { return __hip_atomic_fetch_add(p, v, __ATOMIC_RELAXED, __HIP_MEMORY_SCOPE_AGENT); }
; #define XB_SPIN(cond, bar) do { unsigned _sp = 0; while (cond) { __builtin_amdgcn_s_sleep(1); \
;     if ((++_sp & 255u) == 0u) { if (xb_ld(&(bar)[XB_TMO])) break; if (_sp > XB_SPIN_CAP) { atomicAdd(&(bar)[XB_TMO], 1u); break; } } } } while (0)
; __device__ __forceinline__ void xcd_barrier(const XcdBarrier& b, const int wave) {
;     ...
;             const unsigned og = xb_add(&bar[XB_TOP], 1u);
;             const unsigned tg = og / nx;
;             if (og + 1u == (tg + 1u) * nx) xb_add(&bar[XB_TOPGEN], 1u);
;             else XB_SPIN(xb_ld(&bar[XB_TOPGEN]) == tg, bar);
.LBB0_682:
	s_or_b64 exec, exec, s[8:9]
	s_waitcnt vmcnt(0)
	v_readfirstlane_b32 s6, v2
	s_add_u32 s8, s94, 0x7500
	s_addc_u32 s9, s95, 0
	s_mov_b64 s[10:11], -1
	v_add_u32_e32 v1, s6, v1
	v_add_u32_e32 v4, 1, v1
	v_mov_b32_e32 v2, 4
	v_mul_u32_u24_e32 v0, 5, v0
	v_cmp_ne_u32_e32 vcc, v4, v0
	v_mov_b64_e32 v[0:1], s[8:9]
	s_and_saveexec_b64 s[6:7], vcc
	s_cbranch_execz .LBB0_694
	v_mov_b32_e32 v0, 0
	global_load_dword v1, v0, s[8:9] sc1
	s_mov_b64 s[14:15], 0
	s_waitcnt vmcnt(0)
	v_cmp_eq_u32_e32 vcc, v1, v2
	s_and_saveexec_b64 s[12:13], vcc
	s_cbranch_execz .LBB0_693
	s_add_u32 s10, s94, 0x4200
	s_addc_u32 s11, s95, 0
	s_mov_b32 s24, 1
	s_branch .LBB0_686
